# diff-attention tail loop: exps re-spaced over all 16 PV MFMAs as in the main loop
# speedup vs baseline: 1.0116x; 1.0026x over previous
.LBB0_495:
	s_waitcnt lgkmcnt(14)
	v_mfma_f32_32x32x16_bf16 v[0:15], v[156:159], v[212:215], v[0:15]
	v_exp_f32_e32 v128, v128
	ds_read_b64_tr_b16 v[92:93], v236 offset:32768
	ds_read_b64_tr_b16 v[94:95], v236 offset:33280
	s_waitcnt lgkmcnt(14)
	v_mfma_f32_32x32x16_bf16 v[48:63], v[156:159], v[208:211], v[48:63]
	v_exp_f32_e32 v132, v132
	ds_read_b64_tr_b16 v[108:109], v236 offset:36864
	ds_read_b64_tr_b16 v[110:111], v236 offset:37376
	v_add_u32_e32 v176, s31, v243
	ds_read_b128 v[80:83], v176
	ds_read_b128 v[196:199], v176 offset:512
	s_waitcnt lgkmcnt(14)
	v_mfma_f32_32x32x16_bf16 v[0:15], v[152:155], v[204:207], v[0:15]
	v_exp_f32_e32 v136, v136
	ds_read_b64_tr_b16 v[204:205], v236 offset:33792
	ds_read_b64_tr_b16 v[206:207], v236 offset:34304
	ds_read_b128 v[200:203], v176 offset:2048
	ds_read_b128 v[192:195], v176 offset:2560
	v_mfma_f32_32x32x16_bf16 v[48:63], v[152:155], v[104:107], v[48:63]
	v_exp_f32_e32 v140, v140
	ds_read_b64_tr_b16 v[104:105], v236 offset:37888
	ds_read_b64_tr_b16 v[106:107], v236 offset:38400
	ds_read_b128 v[188:191], v176 offset:4096
	ds_read_b128 v[184:187], v176 offset:4608
	s_waitcnt lgkmcnt(14)
	v_mfma_f32_32x32x16_bf16 v[0:15], v[148:151], v[100:103], v[0:15]
	v_exp_f32_e32 v112, v112
	ds_read_b64_tr_b16 v[100:101], v236 offset:34816
	ds_read_b64_tr_b16 v[102:103], v236 offset:35328
	ds_read_b128 v[180:183], v176 offset:6144
	ds_read_b128 v[176:179], v176 offset:6656
	v_mfma_f32_32x32x16_bf16 v[48:63], v[148:151], v[96:99], v[48:63]
	v_exp_f32_e32 v116, v116
	ds_read_b64_tr_b16 v[96:97], v236 offset:38912
	ds_read_b64_tr_b16 v[98:99], v236 offset:39424
	v_mfma_f32_32x32x16_bf16 v[0:15], v[144:147], v[84:87], v[0:15]
	v_exp_f32_e32 v120, v120
	ds_read_b64_tr_b16 v[84:85], v236 offset:35840
	ds_read_b64_tr_b16 v[86:87], v236 offset:36352
	v_mfma_f32_32x32x16_bf16 v[48:63], v[144:147], v[88:91], v[48:63]
	v_exp_f32_e32 v124, v124
	ds_read_b64_tr_b16 v[88:89], v236 offset:39936
	ds_read_b64_tr_b16 v[90:91], v236 offset:40448
	s_waitcnt lgkmcnt(14)
	v_mfma_f32_32x32x16_bf16 v[16:31], v[156:159], v[92:95], v[16:31]
	v_exp_f32_e32 v129, v129
	v_exp_f32_e32 v130, v130
	v_exp_f32_e32 v131, v131
	v_mfma_f32_32x32x16_bf16 v[32:47], v[156:159], v[108:111], v[32:47]
	v_exp_f32_e32 v133, v133
	v_exp_f32_e32 v134, v134
	v_exp_f32_e32 v135, v135
	v_mfma_f32_32x32x16_bf16 v[16:31], v[152:155], v[204:207], v[16:31]
	v_exp_f32_e32 v137, v137
	v_exp_f32_e32 v138, v138
	v_exp_f32_e32 v139, v139
	s_waitcnt lgkmcnt(12)
	v_mfma_f32_32x32x16_bf16 v[32:47], v[152:155], v[104:107], v[32:47]
	v_exp_f32_e32 v141, v141
	v_exp_f32_e32 v142, v142
	v_exp_f32_e32 v143, v143
	s_waitcnt lgkmcnt(8)
	v_mfma_f32_32x32x16_bf16 v[16:31], v[148:151], v[100:103], v[16:31]
	v_exp_f32_e32 v113, v113
	v_exp_f32_e32 v114, v114
	v_exp_f32_e32 v115, v115
	s_waitcnt lgkmcnt(4)
	v_mfma_f32_32x32x16_bf16 v[32:47], v[148:151], v[96:99], v[32:47]
	v_exp_f32_e32 v117, v117
	v_exp_f32_e32 v118, v118
	v_exp_f32_e32 v119, v119
	s_waitcnt lgkmcnt(2)
	v_mfma_f32_32x32x16_bf16 v[16:31], v[144:147], v[84:87], v[16:31]
	v_exp_f32_e32 v121, v121
	v_exp_f32_e32 v122, v122
	v_exp_f32_e32 v123, v123
	s_waitcnt lgkmcnt(0)
	v_mfma_f32_32x32x16_bf16 v[32:47], v[144:147], v[88:91], v[32:47]
	v_exp_f32_e32 v125, v125
	v_exp_f32_e32 v126, v126
	v_exp_f32_e32 v127, v127
	s_mov_b64 s[22:23], -1
	s_and_b64 vcc, exec, s[16:17]
	s_cbranch_vccz .LBB0_508
	s_waitcnt vmcnt(2) lgkmcnt(0)
	s_barrier
	s_cbranch_execz .LBB0_509

.LBB0_502:
	s_waitcnt lgkmcnt(14)
	v_mfma_f32_32x32x16_bf16 v[0:15], v[156:159], v[212:215], v[0:15]
	v_exp_f32_e32 v96, v96
	ds_read_b64_tr_b16 v[124:125], v236 offset:32768
	ds_read_b64_tr_b16 v[126:127], v236 offset:33280
	s_waitcnt lgkmcnt(14)
	v_mfma_f32_32x32x16_bf16 v[48:63], v[156:159], v[204:207], v[48:63]
	v_exp_f32_e32 v100, v100
	ds_read_b64_tr_b16 v[136:137], v236 offset:36864
	ds_read_b64_tr_b16 v[138:139], v236 offset:37376
	v_add_u32_e32 v176, s33, v243
	ds_read_b128 v[204:207], v176
	ds_read_b128 v[196:199], v176 offset:512
	s_waitcnt lgkmcnt(14)
	v_mfma_f32_32x32x16_bf16 v[0:15], v[152:155], v[208:211], v[0:15]
	v_exp_f32_e32 v104, v104
	ds_read_b64_tr_b16 v[140:141], v236 offset:33792
	ds_read_b64_tr_b16 v[142:143], v236 offset:34304
	ds_read_b128 v[200:203], v176 offset:2048
	ds_read_b128 v[192:195], v176 offset:2560
	v_mfma_f32_32x32x16_bf16 v[48:63], v[152:155], v[132:135], v[48:63]
	v_exp_f32_e32 v108, v108
	ds_read_b64_tr_b16 v[132:133], v236 offset:37888
	ds_read_b64_tr_b16 v[134:135], v236 offset:38400
	ds_read_b128 v[188:191], v176 offset:4096
	ds_read_b128 v[184:187], v176 offset:4608
	s_waitcnt lgkmcnt(14)
	v_mfma_f32_32x32x16_bf16 v[0:15], v[148:151], v[128:131], v[0:15]
	v_exp_f32_e32 v80, v80
	ds_read_b64_tr_b16 v[128:129], v236 offset:34816
	ds_read_b64_tr_b16 v[130:131], v236 offset:35328
	ds_read_b128 v[180:183], v176 offset:6144
	ds_read_b128 v[176:179], v176 offset:6656
	v_mfma_f32_32x32x16_bf16 v[48:63], v[148:151], v[112:115], v[48:63]
	v_exp_f32_e32 v84, v84
	ds_read_b64_tr_b16 v[112:113], v236 offset:38912
	ds_read_b64_tr_b16 v[114:115], v236 offset:39424
	v_mfma_f32_32x32x16_bf16 v[0:15], v[144:147], v[116:119], v[0:15]
	v_exp_f32_e32 v88, v88
	ds_read_b64_tr_b16 v[116:117], v236 offset:35840
	ds_read_b64_tr_b16 v[118:119], v236 offset:36352
	v_mfma_f32_32x32x16_bf16 v[48:63], v[144:147], v[120:123], v[48:63]
	v_exp_f32_e32 v92, v92
	ds_read_b64_tr_b16 v[120:121], v236 offset:39936
	ds_read_b64_tr_b16 v[122:123], v236 offset:40448
	s_waitcnt lgkmcnt(14)
	v_mfma_f32_32x32x16_bf16 v[16:31], v[156:159], v[124:127], v[16:31]
	v_exp_f32_e32 v97, v97
	v_exp_f32_e32 v98, v98
	v_exp_f32_e32 v99, v99
	v_mfma_f32_32x32x16_bf16 v[32:47], v[156:159], v[136:139], v[32:47]
	v_exp_f32_e32 v101, v101
	v_exp_f32_e32 v102, v102
	v_exp_f32_e32 v103, v103
	v_mfma_f32_32x32x16_bf16 v[16:31], v[152:155], v[140:143], v[16:31]
	v_exp_f32_e32 v105, v105
	v_exp_f32_e32 v106, v106
	v_exp_f32_e32 v107, v107
	s_waitcnt lgkmcnt(12)
	v_mfma_f32_32x32x16_bf16 v[32:47], v[152:155], v[132:135], v[32:47]
	v_exp_f32_e32 v109, v109
	v_exp_f32_e32 v110, v110
	v_exp_f32_e32 v111, v111
	s_waitcnt lgkmcnt(8)
	v_mfma_f32_32x32x16_bf16 v[16:31], v[148:151], v[128:131], v[16:31]
	v_exp_f32_e32 v81, v81
	v_exp_f32_e32 v82, v82
	v_exp_f32_e32 v83, v83
	s_waitcnt lgkmcnt(4)
	v_mfma_f32_32x32x16_bf16 v[32:47], v[148:151], v[112:115], v[32:47]
	v_exp_f32_e32 v85, v85
	v_exp_f32_e32 v86, v86
	v_exp_f32_e32 v87, v87
	s_waitcnt lgkmcnt(2)
	v_mfma_f32_32x32x16_bf16 v[16:31], v[144:147], v[116:119], v[16:31]
	v_exp_f32_e32 v89, v89
	v_exp_f32_e32 v90, v90
	v_exp_f32_e32 v91, v91
	s_waitcnt lgkmcnt(0)
	v_mfma_f32_32x32x16_bf16 v[32:47], v[144:147], v[120:123], v[32:47]
	v_exp_f32_e32 v93, v93
	v_exp_f32_e32 v94, v94
	v_exp_f32_e32 v95, v95
	s_mov_b64 s[42:43], -1
	s_and_b64 vcc, exec, s[20:21]
	s_cbranch_vccz .LBB0_510
	s_waitcnt vmcnt(0) lgkmcnt(0)
	s_barrier
	s_cbranch_execz .LBB0_511
